# attention Q-prep: 24 gq/rope-table loads hoisted ahead of the Q loads into fresh registers (9 fewer serialized round trips per item); on top of v50
# speedup vs baseline: 1.0039x; 1.0039x over previous
; DI float bf2f(short v) { return __uint_as_float(((unsigned)(unsigned short)v) << 16); }
; DI int opaque_tid512() { int t = threadIdx.x; asm volatile("" : "+v"(t)); return t; }
; DI void attn_phase(const bf16_t* __restrict__ qraw, const bf16_t* __restrict__ kbuf, const bf16_t* __restrict__ vtb, bf16_t* __restrict__ obuf,
;                    const float* __restrict__ gq, const float* __restrict__ cosT, const float* __restrict__ sinT, bf16_t* sm, int x, int j) {
;     ...
;       const int tid = opaque_tid512(), lane = tid & 63, wave = tid >> 6, r = lane & 31, h = lane >> 5;
;       const int qb = half ? (p & 31) : (63 - (p & 31));
;       const int q0 = qb * 256 + wave * 32;
;       const size_t tok = (size_t)b * S + q0 + r;
;       bf16x8 qf[12];
;       {
;         const bf16_t* qp = qraw + tok * 1536 + hd * QKH + h * 8;
; #pragma unroll
;         for (int st = 0; st < 12; ++st) qf[st] = __builtin_nontemporal_load((const bf16x8*)(qp + st * 16));
;         float ss = 0.f;
; #pragma unroll
;         for (int st = 0; st < 12; ++st) {
; #pragma unroll
;           for (int e = 0; e < 8; ++e) { const float f = bf2f(qf[st][e]); ss += f * f; }
;           u32x4 t = __builtin_bit_cast(u32x4, qf[st]);
;           asm volatile("" : "+v"(t));
;           qf[st] = __builtin_bit_cast(bf16x8, t);
;         }
;         ss += __shfl_xor(ss, 32);
;         const float rq = rsqrtf(ss * (1.f / QKH) + EPS) * (0.07216878364870322f * 1.4426950408889634f);
.LBB0_1280:
	s_xor_b64 s[56:57], s[0:1], -1
	v_mov_b32_e32 v53, v211
	s_and_b64 s[0:1], s[0:1], exec
	s_cselect_b32 s0, s87, s81
	v_ashrrev_i32_e32 v0, 1, v53
	s_lshl_b32 s0, s0, 8
	v_and_b32_e32 v0, 0xffffffe0, v0
	v_add_u32_e32 v186, s0, v0
	v_ashrrev_i32_e32 v187, 31, v186
	v_and_b32_e32 v51, 31, v53
	v_lshl_add_u64 v[184:185], s[10:11], 0, v[186:187]
	v_or_b32_e32 v184, v184, v51
	v_mov_b64_e32 v[2:3], s[12:13]
	v_bfe_u32 v52, v53, 5, 1
	v_mad_u64_u32 v[2:3], s[2:3], v184, s64, v[2:3]
	v_mad_i32_i24 v3, v185, s64, v3
	v_lshlrev_b32_e32 v0, 4, v52
	v_lshl_add_u64 v[2:3], v[2:3], 0, v[0:1]
	v_lshlrev_b32_e32 v208, 5, v52
	v_mov_b32_e32 v209, 0
	v_lshlrev_b64 v[240:241], 7, v[184:185]
	v_lshl_add_u64 v[242:243], s[24:25], 0, v[240:241]
	v_lshl_add_u64 v[244:245], s[26:27], 0, v[240:241]
	v_lshl_add_u64 v[246:247], v[244:245], 0, v[208:209]
	v_lshl_add_u64 v[248:249], v[242:243], 0, v[208:209]
	global_load_dwordx4 v[64:67], v208, s[8:9] offset:16
	global_load_dwordx4 v[68:71], v208, s[8:9]
	global_load_dwordx4 v[72:75], v208, s[8:9] offset:80
	global_load_dwordx4 v[76:79], v208, s[8:9] offset:64
	global_load_dwordx4 v[80:83], v208, s[8:9] offset:144
	global_load_dwordx4 v[84:87], v208, s[8:9] offset:128
	global_load_dwordx4 v[88:91], v208, s[8:9] offset:208
	global_load_dwordx4 v[92:95], v208, s[8:9] offset:192
	global_load_dwordx4 v[96:99], v208, s[8:9] offset:272
	global_load_dwordx4 v[100:103], v208, s[8:9] offset:256
	global_load_dwordx4 v[104:107], v208, s[8:9] offset:336
	global_load_dwordx4 v[108:111], v208, s[8:9] offset:320
	global_load_dwordx4 v[160:163], v208, s[8:9] offset:400
	global_load_dwordx4 v[164:167], v208, s[8:9] offset:384
	global_load_dwordx4 v[168:171], v208, s[8:9] offset:464
	global_load_dwordx4 v[172:175], v208, s[8:9] offset:448
	global_load_dwordx4 v[176:179], v[246:247], off offset:16
	global_load_dwordx4 v[180:183], v[246:247], off
	global_load_dwordx4 v[188:191], v208, s[8:9] offset:528
	global_load_dwordx4 v[192:195], v208, s[8:9] offset:512
	global_load_dwordx4 v[196:199], v[248:249], off offset:16
	global_load_dwordx4 v[200:203], v[248:249], off
	global_load_dwordx4 v[204:207], v208, s[8:9] offset:656
	global_load_dwordx4 v[212:215], v208, s[8:9] offset:640
	global_load_dwordx4 v[46:49], v[2:3], off nt
	global_load_dwordx4 v[42:45], v[2:3], off offset:32 nt
	global_load_dwordx4 v[38:41], v[2:3], off offset:64 nt
	global_load_dwordx4 v[34:37], v[2:3], off offset:96 nt
	global_load_dwordx4 v[30:33], v[2:3], off offset:128 nt
	global_load_dwordx4 v[26:29], v[2:3], off offset:160 nt
	global_load_dwordx4 v[22:25], v[2:3], off offset:192 nt
	global_load_dwordx4 v[18:21], v[2:3], off offset:224 nt
	global_load_dwordx4 v[14:17], v[2:3], off offset:256 nt
	global_load_dwordx4 v[6:9], v[2:3], off offset:288 nt
	global_load_dwordx4 v[10:13], v[2:3], off offset:320 nt
	s_nop 0
	global_load_dwordx4 v[2:5], v[2:3], off offset:352 nt
	s_mov_b32 s92, 1
	v_lshlrev_b32_e32 v187, 3, v52
	s_mov_b32 s31, 0
	s_waitcnt vmcnt(11)
	v_and_b32_e32 v0, 0xffff0000, v46
	v_lshlrev_b32_e32 v50, 16, v46
	v_mul_f32_e32 v0, v0, v0
	v_fmac_f32_e32 v0, v50, v50
	v_lshlrev_b32_e32 v50, 16, v47
	v_fmac_f32_e32 v0, v50, v50
	v_and_b32_e32 v50, 0xffff0000, v47
	v_fmac_f32_e32 v0, v50, v50
	v_lshlrev_b32_e32 v50, 16, v48
	v_fmac_f32_e32 v0, v50, v50
	v_and_b32_e32 v50, 0xffff0000, v48
	v_fmac_f32_e32 v0, v50, v50
	v_lshlrev_b32_e32 v50, 16, v49
	v_fmac_f32_e32 v0, v50, v50
	v_and_b32_e32 v50, 0xffff0000, v49
	v_fmac_f32_e32 v0, v50, v50
	s_waitcnt vmcnt(10)
	v_lshlrev_b32_e32 v50, 16, v42
	v_fmac_f32_e32 v0, v50, v50
	v_and_b32_e32 v50, 0xffff0000, v42
	v_fmac_f32_e32 v0, v50, v50
	v_lshlrev_b32_e32 v50, 16, v43
	v_fmac_f32_e32 v0, v50, v50
	v_and_b32_e32 v50, 0xffff0000, v43
	v_fmac_f32_e32 v0, v50, v50
	v_lshlrev_b32_e32 v50, 16, v44
	v_fmac_f32_e32 v0, v50, v50
	v_and_b32_e32 v50, 0xffff0000, v44
	v_fmac_f32_e32 v0, v50, v50
	v_lshlrev_b32_e32 v50, 16, v45
	v_fmac_f32_e32 v0, v50, v50
	v_and_b32_e32 v50, 0xffff0000, v45
	v_fmac_f32_e32 v0, v50, v50
	s_waitcnt vmcnt(9)
	v_lshlrev_b32_e32 v50, 16, v38
	v_fmac_f32_e32 v0, v50, v50
	v_and_b32_e32 v50, 0xffff0000, v38
	v_fmac_f32_e32 v0, v50, v50
	v_lshlrev_b32_e32 v50, 16, v39
	v_fmac_f32_e32 v0, v50, v50
	v_and_b32_e32 v50, 0xffff0000, v39
	v_fmac_f32_e32 v0, v50, v50
	v_lshlrev_b32_e32 v50, 16, v40
	v_fmac_f32_e32 v0, v50, v50
	v_and_b32_e32 v50, 0xffff0000, v40
	v_fmac_f32_e32 v0, v50, v50
	v_lshlrev_b32_e32 v50, 16, v41
	v_fmac_f32_e32 v0, v50, v50
	v_and_b32_e32 v50, 0xffff0000, v41
	v_fmac_f32_e32 v0, v50, v50
	s_waitcnt vmcnt(8)
	v_lshlrev_b32_e32 v50, 16, v34
	v_fmac_f32_e32 v0, v50, v50
	v_and_b32_e32 v50, 0xffff0000, v34
	v_fmac_f32_e32 v0, v50, v50
	v_lshlrev_b32_e32 v50, 16, v35
	v_fmac_f32_e32 v0, v50, v50
	v_and_b32_e32 v50, 0xffff0000, v35
	v_fmac_f32_e32 v0, v50, v50
	v_lshlrev_b32_e32 v50, 16, v36
	v_fmac_f32_e32 v0, v50, v50
	v_and_b32_e32 v50, 0xffff0000, v36
	v_fmac_f32_e32 v0, v50, v50
	v_lshlrev_b32_e32 v50, 16, v37
	v_fmac_f32_e32 v0, v50, v50
	v_and_b32_e32 v50, 0xffff0000, v37
	v_fmac_f32_e32 v0, v50, v50
	s_waitcnt vmcnt(7)
	v_lshlrev_b32_e32 v50, 16, v30
	v_fmac_f32_e32 v0, v50, v50
	v_and_b32_e32 v50, 0xffff0000, v30
	v_fmac_f32_e32 v0, v50, v50
	v_lshlrev_b32_e32 v50, 16, v31
	v_fmac_f32_e32 v0, v50, v50
	v_and_b32_e32 v50, 0xffff0000, v31
	v_fmac_f32_e32 v0, v50, v50
	v_lshlrev_b32_e32 v50, 16, v32
	v_fmac_f32_e32 v0, v50, v50
	v_and_b32_e32 v50, 0xffff0000, v32
	v_fmac_f32_e32 v0, v50, v50
	v_lshlrev_b32_e32 v50, 16, v33
	v_fmac_f32_e32 v0, v50, v50
	v_and_b32_e32 v50, 0xffff0000, v33
	v_fmac_f32_e32 v0, v50, v50
	s_waitcnt vmcnt(6)
; DI unsigned pack_bf16(float lo, float hi) { f32x2 v = {lo, hi}; bf16v2 b = __builtin_convertvector(v, bf16v2); return __builtin_bit_cast(unsigned, b); }
; DI float bf2f(short v) { return __uint_as_float(((unsigned)(unsigned short)v) << 16); }
; DI void attn_phase(const bf16_t* __restrict__ qraw, const bf16_t* __restrict__ kbuf, const bf16_t* __restrict__ vtb, bf16_t* __restrict__ obuf,
;                    const float* __restrict__ gq, const float* __restrict__ cosT, const float* __restrict__ sinT, bf16_t* sm, int x, int j) {
;     ...
;         for (int st = 0; st < 12; ++st) {
; #pragma unroll
;           for (int e = 0; e < 8; ++e) { const float f = bf2f(qf[st][e]); ss += f * f; }
;           u32x4 t = __builtin_bit_cast(u32x4, qf[st]);
;           asm volatile("" : "+v"(t));
;           qf[st] = __builtin_bit_cast(bf16x8, t);
;         }
;         ss += __shfl_xor(ss, 32);
;         const float rq = rsqrtf(ss * (1.f / QKH) + EPS) * (0.07216878364870322f * 1.4426950408889634f);
;         __builtin_amdgcn_sched_barrier(0);
; #pragma unroll
;         for (int st = 0; st < 8; ++st) {
;           const f32x4 ga = *(const f32x4*)(gq + st * 16 + h * 8), gb = *(const f32x4*)(gq + st * 16 + h * 8 + 4);
;           u32x4 o;
;           o.x = pack_bf16(bf2f(qf[st][0]) * rq * ga.x, bf2f(qf[st][1]) * rq * ga.y);
;           o.y = pack_bf16(bf2f(qf[st][2]) * rq * ga.z, bf2f(qf[st][3]) * rq * ga.w);
;           o.z = pack_bf16(bf2f(qf[st][4]) * rq * gb.x, bf2f(qf[st][5]) * rq * gb.y);
;           o.w = pack_bf16(bf2f(qf[st][6]) * rq * gb.z, bf2f(qf[st][7]) * rq * gb.w);
;           asm volatile("" : "+v"(o));
;           qf[st] = __builtin_bit_cast(bf16x8, o);
;           __builtin_amdgcn_sched_barrier(0);
	v_lshlrev_b32_e32 v50, 16, v26
	v_fmac_f32_e32 v0, v50, v50
	v_and_b32_e32 v50, 0xffff0000, v26
	v_fmac_f32_e32 v0, v50, v50
	v_lshlrev_b32_e32 v50, 16, v27
	v_fmac_f32_e32 v0, v50, v50
	v_and_b32_e32 v50, 0xffff0000, v27
	v_fmac_f32_e32 v0, v50, v50
	v_lshlrev_b32_e32 v50, 16, v28
	v_fmac_f32_e32 v0, v50, v50
	v_and_b32_e32 v50, 0xffff0000, v28
	v_fmac_f32_e32 v0, v50, v50
	v_lshlrev_b32_e32 v50, 16, v29
	v_fmac_f32_e32 v0, v50, v50
	v_and_b32_e32 v50, 0xffff0000, v29
	v_fmac_f32_e32 v0, v50, v50
	s_waitcnt vmcnt(5)
	v_lshlrev_b32_e32 v50, 16, v22
	v_fmac_f32_e32 v0, v50, v50
	v_and_b32_e32 v50, 0xffff0000, v22
	v_fmac_f32_e32 v0, v50, v50
	v_lshlrev_b32_e32 v50, 16, v23
	v_fmac_f32_e32 v0, v50, v50
	v_and_b32_e32 v50, 0xffff0000, v23
	v_fmac_f32_e32 v0, v50, v50
	v_lshlrev_b32_e32 v50, 16, v24
	v_fmac_f32_e32 v0, v50, v50
	v_and_b32_e32 v50, 0xffff0000, v24
	v_fmac_f32_e32 v0, v50, v50
	v_lshlrev_b32_e32 v50, 16, v25
	v_fmac_f32_e32 v0, v50, v50
	v_and_b32_e32 v50, 0xffff0000, v25
	v_fmac_f32_e32 v0, v50, v50
	s_waitcnt vmcnt(4)
	v_lshlrev_b32_e32 v50, 16, v18
	v_fmac_f32_e32 v0, v50, v50
	v_and_b32_e32 v50, 0xffff0000, v18
	v_fmac_f32_e32 v0, v50, v50
	v_lshlrev_b32_e32 v50, 16, v19
	v_fmac_f32_e32 v0, v50, v50
	v_and_b32_e32 v50, 0xffff0000, v19
	v_fmac_f32_e32 v0, v50, v50
	v_lshlrev_b32_e32 v50, 16, v20
	v_fmac_f32_e32 v0, v50, v50
	v_and_b32_e32 v50, 0xffff0000, v20
	v_fmac_f32_e32 v0, v50, v50
	v_lshlrev_b32_e32 v50, 16, v21
	v_fmac_f32_e32 v0, v50, v50
	v_and_b32_e32 v50, 0xffff0000, v21
	v_fmac_f32_e32 v0, v50, v50
	s_waitcnt vmcnt(3)
	v_lshlrev_b32_e32 v50, 16, v14
	v_fmac_f32_e32 v0, v50, v50
	v_and_b32_e32 v50, 0xffff0000, v14
	v_fmac_f32_e32 v0, v50, v50
	v_lshlrev_b32_e32 v50, 16, v15
	v_fmac_f32_e32 v0, v50, v50
	v_and_b32_e32 v50, 0xffff0000, v15
	v_fmac_f32_e32 v0, v50, v50
	v_lshlrev_b32_e32 v50, 16, v16
	v_fmac_f32_e32 v0, v50, v50
	v_and_b32_e32 v50, 0xffff0000, v16
	v_fmac_f32_e32 v0, v50, v50
	v_lshlrev_b32_e32 v50, 16, v17
	v_fmac_f32_e32 v0, v50, v50
	v_and_b32_e32 v50, 0xffff0000, v17
	v_fmac_f32_e32 v0, v50, v50
	s_waitcnt vmcnt(2)
	v_lshlrev_b32_e32 v50, 16, v6
	v_fmac_f32_e32 v0, v50, v50
	v_and_b32_e32 v50, 0xffff0000, v6
	v_fmac_f32_e32 v0, v50, v50
	v_lshlrev_b32_e32 v50, 16, v7
	v_fmac_f32_e32 v0, v50, v50
	v_and_b32_e32 v50, 0xffff0000, v7
	v_fmac_f32_e32 v0, v50, v50
	v_lshlrev_b32_e32 v50, 16, v8
	v_fmac_f32_e32 v0, v50, v50
	v_and_b32_e32 v50, 0xffff0000, v8
	v_fmac_f32_e32 v0, v50, v50
	v_lshlrev_b32_e32 v50, 16, v9
	v_fmac_f32_e32 v0, v50, v50
	v_and_b32_e32 v50, 0xffff0000, v9
	v_fmac_f32_e32 v0, v50, v50
	s_waitcnt vmcnt(1)
	v_lshlrev_b32_e32 v50, 16, v10
	v_fmac_f32_e32 v0, v50, v50
	v_and_b32_e32 v50, 0xffff0000, v10
	v_fmac_f32_e32 v0, v50, v50
	v_lshlrev_b32_e32 v50, 16, v11
	v_fmac_f32_e32 v0, v50, v50
	v_and_b32_e32 v50, 0xffff0000, v11
	v_fmac_f32_e32 v0, v50, v50
	v_lshlrev_b32_e32 v50, 16, v12
	v_fmac_f32_e32 v0, v50, v50
	v_and_b32_e32 v50, 0xffff0000, v12
	v_and_b32_e32 v55, 0xffff0000, v13
	v_lshlrev_b32_e32 v54, 16, v13
	v_fmac_f32_e32 v0, v50, v50
	v_pk_mul_f32 v[54:55], v[54:55], v[54:55]
	v_xor_b32_e32 v50, 32, v219
	v_add_f32_e32 v0, v54, v0
	v_add_f32_e32 v0, v55, v0
	s_waitcnt vmcnt(0)
	v_and_b32_e32 v55, 0xffff0000, v2
	v_lshlrev_b32_e32 v54, 16, v2
	v_pk_mul_f32 v[54:55], v[54:55], v[54:55]
	s_nop 0
	v_add_f32_e32 v0, v54, v0
	v_add_f32_e32 v0, v55, v0
	v_and_b32_e32 v55, 0xffff0000, v3
	v_lshlrev_b32_e32 v54, 16, v3
	v_pk_mul_f32 v[54:55], v[54:55], v[54:55]
	s_nop 0
	v_add_f32_e32 v0, v54, v0
	v_add_f32_e32 v0, v55, v0
	v_and_b32_e32 v55, 0xffff0000, v4
	v_lshlrev_b32_e32 v54, 16, v4
	v_pk_mul_f32 v[54:55], v[54:55], v[54:55]
	s_nop 0
	v_add_f32_e32 v0, v54, v0
	v_add_f32_e32 v0, v55, v0
	v_and_b32_e32 v55, 0xffff0000, v5
	v_lshlrev_b32_e32 v54, 16, v5
	v_pk_mul_f32 v[54:55], v[54:55], v[54:55]
	s_nop 0
	v_add_f32_e32 v0, v54, v0
	v_and_b32_e32 v54, 64, v219
	v_add_u32_e32 v54, 64, v54
	v_cmp_lt_i32_e32 vcc, v50, v54
	v_add_f32_e32 v0, v55, v0
	s_nop 0
	v_cndmask_b32_e32 v50, v219, v50, vcc
	v_lshlrev_b32_e32 v50, 2, v50
	ds_bpermute_b32 v50, v50, v0
	s_waitcnt lgkmcnt(0)
	v_add_f32_e32 v0, v0, v50
	v_fmamk_f32 v0, v0, 0x3baaaaab, v210
	v_cmp_gt_f32_e32 vcc, s29, v0
	v_mul_f32_e32 v50, 0x4b800000, v0
	s_nop 0
	v_cndmask_b32_e32 v0, v0, v50, vcc
	v_rsq_f32_e32 v0, v0
	s_nop 0
	v_mul_f32_e32 v50, 0x45800000, v0
	v_cndmask_b32_e32 v0, v0, v50, vcc
	v_mul_f32_e32 v50, 0x3dd53b94, v0
	v_lshlrev_b32_e32 v0, 5, v52
	v_and_b32_e32 v63, 0xffff0000, v46
	v_lshlrev_b32_e32 v62, 16, v46
	v_pk_mul_f32 v[62:63], v[50:51], v[62:63] op_sel_hi:[0,1]
	s_waitcnt vmcnt(0)
	v_pk_mul_f32 v[58:59], v[68:69], v[62:63]
	s_nop 0
	v_cvt_pk_bf16_f32 v112, v58, v59
	v_and_b32_e32 v59, 0xffff0000, v47
	v_lshlrev_b32_e32 v58, 16, v47
	v_pk_mul_f32 v[46:47], v[50:51], v[58:59] op_sel_hi:[0,1]
	v_pk_mul_f32 v[46:47], v[70:71], v[46:47]
	s_nop 0
	v_cvt_pk_bf16_f32 v113, v46, v47
	v_and_b32_e32 v47, 0xffff0000, v48
	v_lshlrev_b32_e32 v46, 16, v48
	v_pk_mul_f32 v[46:47], v[50:51], v[46:47] op_sel_hi:[0,1]
	v_pk_mul_f32 v[46:47], v[64:65], v[46:47]
	s_nop 0
	v_cvt_pk_bf16_f32 v114, v46, v47
	v_and_b32_e32 v47, 0xffff0000, v49
	v_lshlrev_b32_e32 v46, 16, v49
	v_pk_mul_f32 v[46:47], v[50:51], v[46:47] op_sel_hi:[0,1]
	v_pk_mul_f32 v[46:47], v[66:67], v[46:47]
	s_nop 0
	v_cvt_pk_bf16_f32 v115, v46, v47
	v_and_b32_e32 v59, 0xffff0000, v42
	v_lshlrev_b32_e32 v58, 16, v42
	v_pk_mul_f32 v[58:59], v[50:51], v[58:59] op_sel_hi:[0,1]
	s_waitcnt vmcnt(0)
; DI unsigned pack_bf16(float lo, float hi) { f32x2 v = {lo, hi}; bf16v2 b = __builtin_convertvector(v, bf16v2); return __builtin_bit_cast(unsigned, b); }
; DI float bf2f(short v) { return __uint_as_float(((unsigned)(unsigned short)v) << 16); }
; DI void attn_phase(const bf16_t* __restrict__ qraw, const bf16_t* __restrict__ kbuf, const bf16_t* __restrict__ vtb, bf16_t* __restrict__ obuf,
;                    const float* __restrict__ gq, const float* __restrict__ cosT, const float* __restrict__ sinT, bf16_t* sm, int x, int j) {
;     ...
;         for (int st = 0; st < 8; ++st) {
;           const f32x4 ga = *(const f32x4*)(gq + st * 16 + h * 8), gb = *(const f32x4*)(gq + st * 16 + h * 8 + 4);
;           u32x4 o;
;           o.x = pack_bf16(bf2f(qf[st][0]) * rq * ga.x, bf2f(qf[st][1]) * rq * ga.y);
;           o.y = pack_bf16(bf2f(qf[st][2]) * rq * ga.z, bf2f(qf[st][3]) * rq * ga.w);
;           o.z = pack_bf16(bf2f(qf[st][4]) * rq * gb.x, bf2f(qf[st][5]) * rq * gb.y);
;           o.w = pack_bf16(bf2f(qf[st][6]) * rq * gb.z, bf2f(qf[st][7]) * rq * gb.w);
;           asm volatile("" : "+v"(o));
;           qf[st] = __builtin_bit_cast(bf16x8, o);
;           __builtin_amdgcn_sched_barrier(0);
	v_pk_mul_f32 v[54:55], v[76:77], v[58:59]
	s_nop 0
	v_cvt_pk_bf16_f32 v116, v54, v55
	v_and_b32_e32 v55, 0xffff0000, v43
	v_lshlrev_b32_e32 v54, 16, v43
	v_pk_mul_f32 v[42:43], v[50:51], v[54:55] op_sel_hi:[0,1]
	v_pk_mul_f32 v[42:43], v[78:79], v[42:43]
	s_nop 0
	v_cvt_pk_bf16_f32 v117, v42, v43
	v_and_b32_e32 v43, 0xffff0000, v44
	v_lshlrev_b32_e32 v42, 16, v44
	v_pk_mul_f32 v[42:43], v[50:51], v[42:43] op_sel_hi:[0,1]
	v_pk_mul_f32 v[42:43], v[72:73], v[42:43]
	s_nop 0
	v_cvt_pk_bf16_f32 v118, v42, v43
	v_and_b32_e32 v43, 0xffff0000, v45
	v_lshlrev_b32_e32 v42, 16, v45
	v_pk_mul_f32 v[42:43], v[50:51], v[42:43] op_sel_hi:[0,1]
	v_pk_mul_f32 v[42:43], v[74:75], v[42:43]
	s_nop 0
	v_cvt_pk_bf16_f32 v119, v42, v43
	v_and_b32_e32 v55, 0xffff0000, v38
	v_lshlrev_b32_e32 v54, 16, v38
	v_pk_mul_f32 v[54:55], v[50:51], v[54:55] op_sel_hi:[0,1]
	s_waitcnt vmcnt(0)
	v_pk_mul_f32 v[46:47], v[84:85], v[54:55]
	s_nop 0
	v_cvt_pk_bf16_f32 v120, v46, v47
	v_and_b32_e32 v47, 0xffff0000, v39
	v_lshlrev_b32_e32 v46, 16, v39
	v_pk_mul_f32 v[38:39], v[50:51], v[46:47] op_sel_hi:[0,1]
	v_pk_mul_f32 v[38:39], v[86:87], v[38:39]
	s_nop 0
	v_cvt_pk_bf16_f32 v121, v38, v39
	v_and_b32_e32 v39, 0xffff0000, v40
	v_lshlrev_b32_e32 v38, 16, v40
	v_pk_mul_f32 v[38:39], v[50:51], v[38:39] op_sel_hi:[0,1]
	v_pk_mul_f32 v[38:39], v[80:81], v[38:39]
	s_nop 0
	v_cvt_pk_bf16_f32 v122, v38, v39
	v_and_b32_e32 v39, 0xffff0000, v41
	v_lshlrev_b32_e32 v38, 16, v41
	v_pk_mul_f32 v[38:39], v[50:51], v[38:39] op_sel_hi:[0,1]
	v_pk_mul_f32 v[38:39], v[82:83], v[38:39]
	s_nop 0
	v_cvt_pk_bf16_f32 v123, v38, v39
	v_and_b32_e32 v47, 0xffff0000, v34
	v_lshlrev_b32_e32 v46, 16, v34
	v_pk_mul_f32 v[46:47], v[50:51], v[46:47] op_sel_hi:[0,1]
	s_waitcnt vmcnt(0)
	v_pk_mul_f32 v[42:43], v[92:93], v[46:47]
	s_nop 0
	v_cvt_pk_bf16_f32 v124, v42, v43
	v_and_b32_e32 v43, 0xffff0000, v35
	v_lshlrev_b32_e32 v42, 16, v35
	v_pk_mul_f32 v[34:35], v[50:51], v[42:43] op_sel_hi:[0,1]
	v_pk_mul_f32 v[34:35], v[94:95], v[34:35]
	s_nop 0
	v_cvt_pk_bf16_f32 v125, v34, v35
	v_and_b32_e32 v35, 0xffff0000, v36
	v_lshlrev_b32_e32 v34, 16, v36
	v_pk_mul_f32 v[34:35], v[50:51], v[34:35] op_sel_hi:[0,1]
	v_pk_mul_f32 v[34:35], v[88:89], v[34:35]
	s_nop 0
	v_cvt_pk_bf16_f32 v126, v34, v35
	v_and_b32_e32 v35, 0xffff0000, v37
	v_lshlrev_b32_e32 v34, 16, v37
	v_pk_mul_f32 v[34:35], v[50:51], v[34:35] op_sel_hi:[0,1]
	v_pk_mul_f32 v[34:35], v[90:91], v[34:35]
	s_nop 0
	v_cvt_pk_bf16_f32 v127, v34, v35
	v_and_b32_e32 v43, 0xffff0000, v30
	v_lshlrev_b32_e32 v42, 16, v30
	v_pk_mul_f32 v[42:43], v[50:51], v[42:43] op_sel_hi:[0,1]
	s_waitcnt vmcnt(0)
	v_pk_mul_f32 v[38:39], v[100:101], v[42:43]
	s_nop 0
	v_cvt_pk_bf16_f32 v128, v38, v39
	v_and_b32_e32 v39, 0xffff0000, v31
	v_lshlrev_b32_e32 v38, 16, v31
	v_pk_mul_f32 v[30:31], v[50:51], v[38:39] op_sel_hi:[0,1]
	v_pk_mul_f32 v[30:31], v[102:103], v[30:31]
	s_nop 0
	v_cvt_pk_bf16_f32 v129, v30, v31
	v_and_b32_e32 v31, 0xffff0000, v32
	v_lshlrev_b32_e32 v30, 16, v32
	v_pk_mul_f32 v[30:31], v[50:51], v[30:31] op_sel_hi:[0,1]
	v_pk_mul_f32 v[30:31], v[96:97], v[30:31]
	s_nop 0
	v_cvt_pk_bf16_f32 v130, v30, v31
	v_and_b32_e32 v31, 0xffff0000, v33
	v_lshlrev_b32_e32 v30, 16, v33
	v_pk_mul_f32 v[30:31], v[50:51], v[30:31] op_sel_hi:[0,1]
	v_pk_mul_f32 v[30:31], v[98:99], v[30:31]
	s_nop 0
	v_cvt_pk_bf16_f32 v131, v30, v31
	v_and_b32_e32 v39, 0xffff0000, v26
	v_lshlrev_b32_e32 v38, 16, v26
	v_pk_mul_f32 v[38:39], v[50:51], v[38:39] op_sel_hi:[0,1]
	s_waitcnt vmcnt(0)
	v_pk_mul_f32 v[34:35], v[108:109], v[38:39]
	s_nop 0
	v_cvt_pk_bf16_f32 v132, v34, v35
	v_and_b32_e32 v35, 0xffff0000, v27
	v_lshlrev_b32_e32 v34, 16, v27
	v_pk_mul_f32 v[26:27], v[50:51], v[34:35] op_sel_hi:[0,1]
	v_pk_mul_f32 v[26:27], v[110:111], v[26:27]
	s_nop 0
	v_cvt_pk_bf16_f32 v133, v26, v27
	v_and_b32_e32 v27, 0xffff0000, v28
	v_lshlrev_b32_e32 v26, 16, v28
	v_pk_mul_f32 v[26:27], v[50:51], v[26:27] op_sel_hi:[0,1]
	v_pk_mul_f32 v[26:27], v[104:105], v[26:27]
	s_nop 0
	v_cvt_pk_bf16_f32 v134, v26, v27
	v_and_b32_e32 v27, 0xffff0000, v29
	v_lshlrev_b32_e32 v26, 16, v29
	v_pk_mul_f32 v[26:27], v[50:51], v[26:27] op_sel_hi:[0,1]
	v_pk_mul_f32 v[26:27], v[106:107], v[26:27]
	s_nop 0
	v_cvt_pk_bf16_f32 v135, v26, v27
	v_and_b32_e32 v35, 0xffff0000, v22
	v_lshlrev_b32_e32 v34, 16, v22
	v_pk_mul_f32 v[34:35], v[50:51], v[34:35] op_sel_hi:[0,1]
	s_waitcnt vmcnt(0)
	v_pk_mul_f32 v[30:31], v[164:165], v[34:35]
	s_nop 0
	v_cvt_pk_bf16_f32 v136, v30, v31
	v_and_b32_e32 v31, 0xffff0000, v23
	v_lshlrev_b32_e32 v30, 16, v23
	v_pk_mul_f32 v[22:23], v[50:51], v[30:31] op_sel_hi:[0,1]
	v_pk_mul_f32 v[22:23], v[166:167], v[22:23]
	s_nop 0
	v_cvt_pk_bf16_f32 v137, v22, v23
	v_and_b32_e32 v23, 0xffff0000, v24
	v_lshlrev_b32_e32 v22, 16, v24
	v_pk_mul_f32 v[22:23], v[50:51], v[22:23] op_sel_hi:[0,1]
	v_pk_mul_f32 v[22:23], v[160:161], v[22:23]
	s_nop 0
	v_cvt_pk_bf16_f32 v138, v22, v23
	v_and_b32_e32 v23, 0xffff0000, v25
	v_lshlrev_b32_e32 v22, 16, v25
	v_pk_mul_f32 v[22:23], v[50:51], v[22:23] op_sel_hi:[0,1]
	v_pk_mul_f32 v[22:23], v[162:163], v[22:23]
	s_nop 0
	v_cvt_pk_bf16_f32 v139, v22, v23
	v_and_b32_e32 v31, 0xffff0000, v18
	v_lshlrev_b32_e32 v30, 16, v18
	v_pk_mul_f32 v[30:31], v[50:51], v[30:31] op_sel_hi:[0,1]
	s_waitcnt vmcnt(0)
; DI unsigned pack_bf16(float lo, float hi) { f32x2 v = {lo, hi}; bf16v2 b = __builtin_convertvector(v, bf16v2); return __builtin_bit_cast(unsigned, b); }
; DI void attn_phase(const bf16_t* __restrict__ qraw, const bf16_t* __restrict__ kbuf, const bf16_t* __restrict__ vtb, bf16_t* __restrict__ obuf,
;                    const float* __restrict__ gq, const float* __restrict__ cosT, const float* __restrict__ sinT, bf16_t* sm, int x, int j) {
;     ...
;         for (int st = 0; st < 8; ++st) {
;           const f32x4 ga = *(const f32x4*)(gq + st * 16 + h * 8), gb = *(const f32x4*)(gq + st * 16 + h * 8 + 4);
;           u32x4 o;
;           o.x = pack_bf16(bf2f(qf[st][0]) * rq * ga.x, bf2f(qf[st][1]) * rq * ga.y);
;           o.y = pack_bf16(bf2f(qf[st][2]) * rq * ga.z, bf2f(qf[st][3]) * rq * ga.w);
;           o.z = pack_bf16(bf2f(qf[st][4]) * rq * gb.x, bf2f(qf[st][5]) * rq * gb.y);
;           o.w = pack_bf16(bf2f(qf[st][6]) * rq * gb.z, bf2f(qf[st][7]) * rq * gb.w);
;           asm volatile("" : "+v"(o));
;           qf[st] = __builtin_bit_cast(bf16x8, o);
;           __builtin_amdgcn_sched_barrier(0);
;         }
; #pragma unroll
;         for (int st = 8; st < 10; ++st) {
;           const int jb = (st - 8) * 16 + h * 8;
;           u32x4 o1, o2;
; #pragma unroll
;           for (int hf = 0; hf < 2; ++hf) {
;             const f32x4 g1 = *(const f32x4*)(gq + 128 + jb + 4 * hf), g2 = *(const f32x4*)(gq + 160 + jb + 4 * hf);
;             const f32x4 cc = *(const f32x4*)(cosT + tok * 32 + jb + 4 * hf), sn = *(const f32x4*)(sinT + tok * 32 + jb + 4 * hf);
;             float y1[4], y2[4];
; #pragma unroll
;             for (int e = 0; e < 4; ++e) {
;               const float x1 = bf2f(qf[st][4 * hf + e]) * rq * g1[e], x2 = bf2f(qf[st + 2][4 * hf + e]) * rq * g2[e];
;               y1[e] = x1 * cc[e] - x2 * sn[e]; y2[e] = x2 * cc[e] + x1 * sn[e];
;             }
;             if (hf == 0) { o1.x = pack_bf16(y1[0], y1[1]); o1.y = pack_bf16(y1[2], y1[3]); o2.x = pack_bf16(y2[0], y2[1]); o2.y = pack_bf16(y2[2], y2[3]); }
;             else { o1.z = pack_bf16(y1[0], y1[1]); o1.w = pack_bf16(y1[2], y1[3]); o2.z = pack_bf16(y2[0], y2[1]); o2.w = pack_bf16(y2[2], y2[3]); }
;           }
;           asm volatile("" : "+v"(o1), "+v"(o2));
;           qf[st] = __builtin_bit_cast(bf16x8, o1); qf[st + 2] = __builtin_bit_cast(bf16x8, o2);
	v_pk_mul_f32 v[26:27], v[172:173], v[30:31]
	s_nop 0
	v_cvt_pk_bf16_f32 v140, v26, v27
	v_and_b32_e32 v27, 0xffff0000, v19
	v_lshlrev_b32_e32 v26, 16, v19
	v_pk_mul_f32 v[18:19], v[50:51], v[26:27] op_sel_hi:[0,1]
	v_pk_mul_f32 v[18:19], v[174:175], v[18:19]
	s_nop 0
	v_cvt_pk_bf16_f32 v141, v18, v19
	v_and_b32_e32 v19, 0xffff0000, v20
	v_lshlrev_b32_e32 v18, 16, v20
	v_pk_mul_f32 v[18:19], v[50:51], v[18:19] op_sel_hi:[0,1]
	v_pk_mul_f32 v[18:19], v[168:169], v[18:19]
	s_nop 0
	v_cvt_pk_bf16_f32 v142, v18, v19
	v_and_b32_e32 v19, 0xffff0000, v21
	v_lshlrev_b32_e32 v18, 16, v21
	v_pk_mul_f32 v[18:19], v[50:51], v[18:19] op_sel_hi:[0,1]
	v_pk_mul_f32 v[18:19], v[170:171], v[18:19]
	s_nop 0
	v_cvt_pk_bf16_f32 v143, v18, v19
	v_lshlrev_b64 v[18:19], 7, v[184:185]
	v_lshl_add_u64 v[20:21], s[24:25], 0, v[18:19]
	v_lshl_add_u64 v[18:19], s[26:27], 0, v[18:19]
	v_lshl_add_u64 v[36:37], v[18:19], 0, v[0:1]
	v_lshl_add_u64 v[34:35], v[20:21], 0, v[0:1]
	v_and_b32_e32 v59, 0xffff0000, v15
	v_lshlrev_b32_e32 v58, 16, v15
	v_pk_mul_f32 v[58:59], v[50:51], v[58:59] op_sel_hi:[0,1]
	v_and_b32_e32 v15, 0xffff0000, v14
	v_lshlrev_b32_e32 v14, 16, v14
	v_pk_mul_f32 v[14:15], v[50:51], v[14:15] op_sel_hi:[0,1]
	s_waitcnt vmcnt(4)
	v_pk_mul_f32 v[44:45], v[194:195], v[58:59]
	v_and_b32_e32 v59, 0xffff0000, v11
	v_lshlrev_b32_e32 v58, 16, v11
	v_and_b32_e32 v11, 0xffff0000, v10
	v_lshlrev_b32_e32 v10, 16, v10
	v_pk_mul_f32 v[10:11], v[50:51], v[10:11] op_sel_hi:[0,1]
	s_waitcnt vmcnt(0)
	v_pk_mul_f32 v[10:11], v[212:213], v[10:11]
	v_pk_mul_f32 v[14:15], v[192:193], v[14:15]
	v_pk_mul_f32 v[42:43], v[200:201], v[10:11]
	v_pk_mul_f32 v[10:11], v[180:181], v[10:11]
	v_pk_fma_f32 v[42:43], v[180:181], v[14:15], v[42:43]
	v_pk_fma_f32 v[10:11], v[200:201], v[14:15], v[10:11] neg_lo:[0,0,1] neg_hi:[0,0,1]
	v_and_b32_e32 v15, 0xffff0000, v12
	v_lshlrev_b32_e32 v14, 16, v12
	v_cvt_pk_bf16_f32 v148, v10, v11
	v_and_b32_e32 v11, 0xffff0000, v16
	v_lshlrev_b32_e32 v10, 16, v16
	v_pk_mul_f32 v[14:15], v[50:51], v[14:15] op_sel_hi:[0,1]
	v_pk_mul_f32 v[10:11], v[50:51], v[10:11] op_sel_hi:[0,1]
	v_pk_mul_f32 v[14:15], v[204:205], v[14:15]
	v_pk_mul_f32 v[10:11], v[188:189], v[10:11]
	v_pk_mul_f32 v[26:27], v[196:197], v[14:15]
	v_pk_mul_f32 v[14:15], v[176:177], v[14:15]
	v_pk_mul_f32 v[58:59], v[50:51], v[58:59] op_sel_hi:[0,1]
	v_pk_fma_f32 v[26:27], v[176:177], v[10:11], v[26:27]
	v_pk_fma_f32 v[10:11], v[196:197], v[10:11], v[14:15] neg_lo:[0,0,1] neg_hi:[0,0,1]
	v_and_b32_e32 v15, 0xffff0000, v13
	v_lshlrev_b32_e32 v14, 16, v13
	v_pk_mul_f32 v[56:57], v[214:215], v[58:59]
	v_cvt_pk_bf16_f32 v150, v10, v11
	v_and_b32_e32 v11, 0xffff0000, v17
	v_lshlrev_b32_e32 v10, 16, v17
	v_pk_mul_f32 v[12:13], v[50:51], v[14:15] op_sel_hi:[0,1]
	v_pk_mul_f32 v[58:59], v[202:203], v[56:57]
	v_pk_mul_f32 v[10:11], v[50:51], v[10:11] op_sel_hi:[0,1]
	v_pk_mul_f32 v[12:13], v[206:207], v[12:13]
	v_pk_fma_f32 v[58:59], v[182:183], v[44:45], v[58:59]
	v_pk_mul_f32 v[40:41], v[182:183], v[56:57]
	v_pk_mul_f32 v[10:11], v[190:191], v[10:11]
	v_pk_mul_f32 v[14:15], v[198:199], v[12:13]
	v_pk_mul_f32 v[12:13], v[178:179], v[12:13]
	v_pk_fma_f32 v[40:41], v[202:203], v[44:45], v[40:41] neg_lo:[0,0,1] neg_hi:[0,0,1]
	v_pk_fma_f32 v[14:15], v[178:179], v[10:11], v[14:15]
	v_pk_fma_f32 v[10:11], v[198:199], v[10:11], v[12:13] neg_lo:[0,0,1] neg_hi:[0,0,1]
	v_cvt_pk_bf16_f32 v149, v40, v41
	v_cvt_pk_bf16_f32 v144, v42, v43
	v_cvt_pk_bf16_f32 v145, v58, v59
	v_cvt_pk_bf16_f32 v146, v26, v27
	v_cvt_pk_bf16_f32 v147, v14, v15
	v_cvt_pk_bf16_f32 v151, v10, v11
	global_load_dwordx4 v[14:17], v[36:37], off offset:80
	global_load_dwordx4 v[22:25], v[36:37], off offset:64
	global_load_dwordx4 v[26:29], v0, s[8:9] offset:592
	global_load_dwordx4 v[30:33], v0, s[8:9] offset:576
	global_load_dwordx4 v[10:13], v[34:35], off offset:80
	s_nop 0
	global_load_dwordx4 v[34:37], v[34:35], off offset:64
	s_nop 0
	global_load_dwordx4 v[18:21], v0, s[8:9] offset:720
	global_load_dwordx4 v[38:41], v0, s[8:9] offset:704
	v_and_b32_e32 v43, 0xffff0000, v7
	v_lshlrev_b32_e32 v42, 16, v7
	v_pk_mul_f32 v[42:43], v[50:51], v[42:43] op_sel_hi:[0,1]
	v_and_b32_e32 v7, 0xffff0000, v6
	v_lshlrev_b32_e32 v6, 16, v6
	v_pk_mul_f32 v[6:7], v[50:51], v[6:7] op_sel_hi:[0,1]
	s_waitcnt vmcnt(4)
	v_pk_mul_f32 v[32:33], v[32:33], v[42:43]
	v_and_b32_e32 v43, 0xffff0000, v3
	v_lshlrev_b32_e32 v42, 16, v3
	v_and_b32_e32 v3, 0xffff0000, v2
	v_lshlrev_b32_e32 v2, 16, v2
	v_pk_mul_f32 v[2:3], v[50:51], v[2:3] op_sel_hi:[0,1]
	s_waitcnt vmcnt(0)
; DI unsigned pack_bf16(float lo, float hi) { f32x2 v = {lo, hi}; bf16v2 b = __builtin_convertvector(v, bf16v2); return __builtin_bit_cast(unsigned, b); }
; DI void attn_phase(const bf16_t* __restrict__ qraw, const bf16_t* __restrict__ kbuf, const bf16_t* __restrict__ vtb, bf16_t* __restrict__ obuf,
;                    const float* __restrict__ gq, const float* __restrict__ cosT, const float* __restrict__ sinT, bf16_t* sm, int x, int j) {
;     ...
;             for (int e = 0; e < 4; ++e) {
;               const float x1 = bf2f(qf[st][4 * hf + e]) * rq * g1[e], x2 = bf2f(qf[st + 2][4 * hf + e]) * rq * g2[e];
;               y1[e] = x1 * cc[e] - x2 * sn[e]; y2[e] = x2 * cc[e] + x1 * sn[e];
;             }
;             if (hf == 0) { o1.x = pack_bf16(y1[0], y1[1]); o1.y = pack_bf16(y1[2], y1[3]); o2.x = pack_bf16(y2[0], y2[1]); o2.y = pack_bf16(y2[2], y2[3]); }
;             else { o1.z = pack_bf16(y1[0], y1[1]); o1.w = pack_bf16(y1[2], y1[3]); o2.z = pack_bf16(y2[0], y2[1]); o2.w = pack_bf16(y2[2], y2[3]); }
;           }
;           asm volatile("" : "+v"(o1), "+v"(o2));
;           qf[st] = __builtin_bit_cast(bf16x8, o1); qf[st + 2] = __builtin_bit_cast(bf16x8, o2);
;           __builtin_amdgcn_sched_barrier(0);
;         }
;       }
;       f32x16 oacc[4];
; #pragma unroll
;       for (int mt = 0; mt < 4; ++mt)
; #pragma unroll
;         for (int i = 0; i < 16; ++i) oacc[mt][i] = 0.f;
;       float m_run = -1e30f, l_run = 0.f;
;       const int nkt = 4 * qb + 4;
;       const bf16_t* kg = kbuf + (size_t)bh * S * QKH;
;       const bf16_t* vg = vtb + (size_t)bh * VH * SV;
;       u32x4 rk[3], rv[2];
;       const unsigned kg_off0 = (unsigned)(tid >> 3) * QKH + (unsigned)(tid & 7) * 8u;
;       const unsigned vg_off0 = (unsigned)(tid >> 3) * (unsigned)SV + (unsigned)(tid & 7) * 8u;
;       const unsigned kl_off = (unsigned)(tid >> 3) * KLS + (unsigned)(tid & 7) * 8u;
;       const unsigned vl_off = (unsigned)(tid >> 3) * VLS + (unsigned)(tid & 7) * 8u;
;     ...
;       ALOAD(0);
;     ...
;       ASTORE(0);
;       __syncthreads();
;       for (int kt = 0; kt < nkt; ++kt) {
;         const bf16_t* smk = sm + (kt & 1) * ATT_STG_EL;
;         const bf16_t* smv = smk + K_EL;
;         const bool act_tile = (kt * 64 <= q0 + 31);
;         if (!act_tile && kt + 1 < nkt) ALOAD(kt + 1);
;         __builtin_amdgcn_sched_barrier(0);
;         if (act_tile) {
	v_pk_mul_f32 v[2:3], v[38:39], v[2:3]
	v_pk_mul_f32 v[6:7], v[30:31], v[6:7]
	v_pk_mul_f32 v[30:31], v[34:35], v[2:3]
	v_pk_mul_f32 v[2:3], v[22:23], v[2:3]
	v_pk_fma_f32 v[30:31], v[22:23], v[6:7], v[30:31]
	v_pk_fma_f32 v[2:3], v[34:35], v[6:7], v[2:3] neg_lo:[0,0,1] neg_hi:[0,0,1]
	v_and_b32_e32 v7, 0xffff0000, v4
	v_lshlrev_b32_e32 v6, 16, v4
	v_cvt_pk_bf16_f32 v156, v2, v3
	v_and_b32_e32 v3, 0xffff0000, v8
	v_lshlrev_b32_e32 v2, 16, v8
	v_pk_mul_f32 v[6:7], v[50:51], v[6:7] op_sel_hi:[0,1]
	v_pk_mul_f32 v[2:3], v[50:51], v[2:3] op_sel_hi:[0,1]
	v_pk_mul_f32 v[6:7], v[18:19], v[6:7]
	v_pk_mul_f32 v[2:3], v[26:27], v[2:3]
	v_pk_mul_f32 v[18:19], v[10:11], v[6:7]
	v_pk_mul_f32 v[6:7], v[14:15], v[6:7]
	v_pk_mul_f32 v[42:43], v[50:51], v[42:43] op_sel_hi:[0,1]
	v_pk_fma_f32 v[18:19], v[14:15], v[2:3], v[18:19]
	v_pk_fma_f32 v[2:3], v[10:11], v[2:3], v[6:7] neg_lo:[0,0,1] neg_hi:[0,0,1]
	v_and_b32_e32 v7, 0xffff0000, v5
	v_lshlrev_b32_e32 v6, 16, v5
	v_pk_mul_f32 v[40:41], v[40:41], v[42:43]
	v_cvt_pk_bf16_f32 v158, v2, v3
	v_and_b32_e32 v3, 0xffff0000, v9
	v_lshlrev_b32_e32 v2, 16, v9
	v_pk_mul_f32 v[4:5], v[50:51], v[6:7] op_sel_hi:[0,1]
	v_pk_mul_f32 v[42:43], v[36:37], v[40:41]
	v_pk_mul_f32 v[2:3], v[50:51], v[2:3] op_sel_hi:[0,1]
	v_pk_mul_f32 v[4:5], v[20:21], v[4:5]
	v_pk_fma_f32 v[42:43], v[24:25], v[32:33], v[42:43]
	v_pk_mul_f32 v[24:25], v[24:25], v[40:41]
	v_pk_mul_f32 v[2:3], v[28:29], v[2:3]
	v_pk_mul_f32 v[6:7], v[12:13], v[4:5]
	v_pk_mul_f32 v[4:5], v[16:17], v[4:5]
	v_pk_fma_f32 v[24:25], v[36:37], v[32:33], v[24:25] neg_lo:[0,0,1] neg_hi:[0,0,1]
	v_pk_fma_f32 v[6:7], v[16:17], v[2:3], v[6:7]
	v_pk_fma_f32 v[2:3], v[12:13], v[2:3], v[4:5] neg_lo:[0,0,1] neg_hi:[0,0,1]
	v_cvt_pk_bf16_f32 v157, v24, v25
	v_cvt_pk_bf16_f32 v152, v30, v31
	v_cvt_pk_bf16_f32 v153, v42, v43
	v_cvt_pk_bf16_f32 v154, v18, v19
	v_cvt_pk_bf16_f32 v155, v6, v7
	v_cvt_pk_bf16_f32 v159, v2, v3
	v_ashrrev_i32_e32 v8, 3, v53
	s_movk_i32 s1, 0xc0
	v_lshlrev_b32_e32 v2, 3, v53
	v_mul_lo_u32 v0, v8, s1
	v_and_b32_e32 v2, 56, v2
	s_movk_i32 s1, 0x4040
	v_or_b32_e32 v192, v0, v2
	v_mul_lo_u32 v0, v8, s1
	v_or_b32_e32 v193, v0, v2
	v_mov_b32_e32 v0, v192
	v_mov_b32_e32 v4, v193
	s_movk_i32 s1, 0xc8
	v_mov_b32_e32 v5, v1
	v_mad_u64_u32 v[188:189], s[2:3], v8, s1, v[2:3]
	v_lshl_add_u64 v[6:7], v[0:1], 1, s[38:39]
	v_lshl_add_u64 v[2:3], v[4:5], 1, s[70:71]
	global_load_dwordx4 v[160:163], v[6:7], off
	global_load_dwordx4 v[172:175], v[2:3], off
	v_add_u32_e32 v6, 64, v0
	v_mov_b32_e32 v7, v1
	v_lshl_add_u64 v[6:7], v[6:7], 1, s[38:39]
	v_add_u32_e32 v0, 0x80, v0
	global_load_dwordx4 v[164:167], v[6:7], off
	v_lshl_add_u64 v[6:7], v[0:1], 1, s[38:39]
	global_load_dwordx4 v[168:171], v[6:7], off
	v_add_u32_e32 v0, 0x101000, v4
	v_lshl_add_u64 v[2:3], v[0:1], 1, s[70:71]
	global_load_dwordx4 v[176:179], v[2:3], off
	v_lshl_add_u32 v0, v188, 1, 0
	v_mov_b32_e32 v14, v1
	v_mov_b32_e32 v15, v1
	v_mul_u32_u24_e32 v195, 0x190, v51
	v_mul_u32_u24_e32 v191, 0x90, v51
	v_or_b32_e32 v190, v186, v51
	v_lshlrev_b32_e32 v189, 2, v52
	v_mov_b32_e32 v2, v1
	v_mov_b32_e32 v3, v1
	v_mov_b32_e32 v4, v1
	v_mov_b32_e32 v6, v1
	v_mov_b32_e32 v7, v1
	v_mov_b32_e32 v9, v1
	v_mov_b32_e32 v10, v1
	v_mov_b32_e32 v11, v1
	v_mov_b32_e32 v12, v1
	v_mov_b32_e32 v13, v1
	v_or_b32_e32 v196, 31, v186
	s_or_b32 s90, s0, 0xc0
	v_mov_b32_e32 v198, 0
	v_mov_b32_e32 v199, 0xf149f2ca
	v_mov_b32_e32 v197, 0
	s_mov_b64 s[54:55], s[58:59]
	s_mov_b64 s[84:85], s[14:15]
	s_waitcnt vmcnt(4)
	ds_write_b128 v0, v[160:163]
	s_waitcnt vmcnt(2)
	ds_write_b128 v0, v[164:167] offset:128
	s_waitcnt vmcnt(1)
	ds_write_b128 v0, v[168:171] offset:256
	v_lshlrev_b32_e32 v0, 7, v8
	v_sub_u32_e32 v194, v188, v0
	s_mov_b32 s98, 0
	v_lshl_add_u32 v0, v194, 1, 0
	ds_write_b128 v0, v[172:175] offset:25600
	s_waitcnt vmcnt(0)
	ds_write_b128 v0, v[176:179] offset:34816
	v_mov_b32_e32 v0, v1
	v_mov_b32_e32 v8, v1
	v_mov_b64_e32 v[30:31], v[14:15]
	v_mov_b64_e32 v[46:47], v[14:15]
	v_mov_b64_e32 v[62:63], v[14:15]
	v_mov_b64_e32 v[78:79], v[14:15]
	v_mov_b64_e32 v[28:29], v[12:13]
	v_mov_b64_e32 v[26:27], v[10:11]
	v_mov_b64_e32 v[24:25], v[8:9]
	v_mov_b64_e32 v[22:23], v[6:7]
	v_mov_b64_e32 v[20:21], v[4:5]
	v_mov_b64_e32 v[18:19], v[2:3]
	v_mov_b64_e32 v[16:17], v[0:1]
	v_mov_b64_e32 v[44:45], v[12:13]
	v_mov_b64_e32 v[42:43], v[10:11]
	v_mov_b64_e32 v[40:41], v[8:9]
	v_mov_b64_e32 v[38:39], v[6:7]
	v_mov_b64_e32 v[36:37], v[4:5]
	v_mov_b64_e32 v[34:35], v[2:3]
	v_mov_b64_e32 v[32:33], v[0:1]
	v_mov_b64_e32 v[60:61], v[12:13]
	v_mov_b64_e32 v[58:59], v[10:11]
	v_mov_b64_e32 v[56:57], v[8:9]
	v_mov_b64_e32 v[54:55], v[6:7]
	v_mov_b64_e32 v[52:53], v[4:5]
	v_mov_b64_e32 v[50:51], v[2:3]
	v_mov_b64_e32 v[48:49], v[0:1]
	v_mov_b64_e32 v[76:77], v[12:13]
	v_mov_b64_e32 v[74:75], v[10:11]
	v_mov_b64_e32 v[72:73], v[8:9]
	v_mov_b64_e32 v[70:71], v[6:7]
	v_mov_b64_e32 v[68:69], v[4:5]
	v_mov_b64_e32 v[66:67], v[2:3]
	v_mov_b64_e32 v[64:65], v[0:1]
	s_waitcnt lgkmcnt(0)
	s_barrier
	v_cmp_le_i32_e32 vcc, s31, v196
	v_cmp_gt_i32_e64 s[0:1], s31, v196
	s_and_saveexec_b64 s[2:3], s[0:1]
	s_cbranch_execz .LBB0_1282
